# nsa_compressed_branch_softmax_rewrite
# speedup vs baseline: 1.0073x; 1.0073x over previous
.LBB0_445:
	v_bfe_u32 v84, v75, 4, 2
	v_subrev_u32_e32 v241, 31, v78
	v_lshlrev_b32_e32 v84, 3, v84
	v_lshrrev_b32_e32 v241, 4, v241
	v_cmp_lt_i32_e32 vcc, 30, v78
	v_add_u32_e32 v241, 1, v241
	v_and_b32_e32 v116, 64, v174
	v_xor_b32_e32 v242, 16, v174
	v_cndmask_b32_e32 v241, 0, v241, vcc
	v_add_u32_e32 v116, 64, v116
	v_xor_b32_e32 v243, 32, v174
	v_sub_u32_e32 v241, v241, v84
	v_cmp_lt_i32_e32 vcc, v242, v116
	v_readlane_b32 s98, v254, 39
	v_readlane_b32 s15, v254, 38
	v_cndmask_b32_e32 v242, v174, v242, vcc
	v_cmp_lt_i32_e32 vcc, v243, v116
	v_readlane_b32 s65, v254, 31
	v_lshlrev_b32_e32 v108, 2, v242
	v_cndmask_b32_e32 v243, v174, v243, vcc
	s_lshr_b32 s98, s98, 4
	s_add_i32 s98, s98, 64
	s_lshr_b32 s98, s98, 6
	v_lshlrev_b32_e32 v109, 2, v243
	v_mov_b32_e32 v240, 0xf149f2ca
	v_cmp_gt_i32_e64 s[0:1], v241, 0
	v_cmp_gt_i32_e64 s[2:3], v241, 1
	v_cmp_gt_i32_e64 s[4:5], v241, 2
	v_cmp_gt_i32_e64 s[6:7], v241, 3
	v_cndmask_b32_e64 v68, v102, v68, s[0:1]
	v_cndmask_b32_e64 v69, v102, v69, s[2:3]
	v_cndmask_b32_e64 v70, v102, v70, s[4:5]
	v_cndmask_b32_e64 v71, v102, v71, s[6:7]
	v_max3_f32 v240, v240, v68, v69
	v_max3_f32 v240, v240, v70, v71
	v_add_u32_e32 v245, 0xfffffffc, v241
	v_cmp_gt_i32_e64 s[0:1], v245, 0
	v_cmp_gt_i32_e64 s[2:3], v245, 1
	v_cmp_gt_i32_e64 s[4:5], v245, 2
	v_cmp_gt_i32_e64 s[6:7], v245, 3
	v_cndmask_b32_e64 v64, v102, v64, s[0:1]
	v_cndmask_b32_e64 v65, v102, v65, s[2:3]
	v_cndmask_b32_e64 v66, v102, v66, s[4:5]
	v_cndmask_b32_e64 v67, v102, v67, s[6:7]
	v_max3_f32 v240, v240, v64, v65
	v_max3_f32 v240, v240, v66, v67
	v_add_u32_e32 v245, 0xffffffe0, v241
	v_cmp_gt_i32_e64 s[0:1], v245, 0
	v_cmp_gt_i32_e64 s[2:3], v245, 1
	v_cmp_gt_i32_e64 s[4:5], v245, 2
	v_cmp_gt_i32_e64 s[6:7], v245, 3
	v_cndmask_b32_e64 v60, v102, v60, s[0:1]
	v_cndmask_b32_e64 v61, v102, v61, s[2:3]
	v_cndmask_b32_e64 v62, v102, v62, s[4:5]
	v_cndmask_b32_e64 v63, v102, v63, s[6:7]
	v_max3_f32 v240, v240, v60, v61
	v_max3_f32 v240, v240, v62, v63
	v_add_u32_e32 v245, 0xffffffdc, v241
	v_cmp_gt_i32_e64 s[0:1], v245, 0
	v_cmp_gt_i32_e64 s[2:3], v245, 1
	v_cmp_gt_i32_e64 s[4:5], v245, 2
	v_cmp_gt_i32_e64 s[6:7], v245, 3
	v_cndmask_b32_e64 v56, v102, v56, s[0:1]
	v_cndmask_b32_e64 v57, v102, v57, s[2:3]
	v_cndmask_b32_e64 v58, v102, v58, s[4:5]
	v_cndmask_b32_e64 v59, v102, v59, s[6:7]
	v_max3_f32 v240, v240, v56, v57
	v_max3_f32 v240, v240, v58, v59
	s_cmp_le_u32 s98, 1
	s_cbranch_scc1 .Lnsa_cs_max_done
	v_add_u32_e32 v245, 0xffffffc0, v241
	v_cmp_gt_i32_e64 s[0:1], v245, 0
	v_cmp_gt_i32_e64 s[2:3], v245, 1
	v_cmp_gt_i32_e64 s[4:5], v245, 2
	v_cmp_gt_i32_e64 s[6:7], v245, 3
	v_cndmask_b32_e64 v52, v102, v52, s[0:1]
	v_cndmask_b32_e64 v53, v102, v53, s[2:3]
	v_cndmask_b32_e64 v54, v102, v54, s[4:5]
	v_cndmask_b32_e64 v55, v102, v55, s[6:7]
	v_max3_f32 v240, v240, v52, v53
	v_max3_f32 v240, v240, v54, v55
	v_add_u32_e32 v245, 0xffffffbc, v241
	v_cmp_gt_i32_e64 s[0:1], v245, 0
	v_cmp_gt_i32_e64 s[2:3], v245, 1
	v_cmp_gt_i32_e64 s[4:5], v245, 2
	v_cmp_gt_i32_e64 s[6:7], v245, 3
	v_cndmask_b32_e64 v36, v102, v36, s[0:1]
	v_cndmask_b32_e64 v37, v102, v37, s[2:3]
	v_cndmask_b32_e64 v38, v102, v38, s[4:5]
	v_cndmask_b32_e64 v39, v102, v39, s[6:7]
	v_max3_f32 v240, v240, v36, v37
	v_max3_f32 v240, v240, v38, v39
	v_add_u32_e32 v245, 0xffffffa0, v241
	v_cmp_gt_i32_e64 s[0:1], v245, 0
	v_cmp_gt_i32_e64 s[2:3], v245, 1
	v_cmp_gt_i32_e64 s[4:5], v245, 2
	v_cmp_gt_i32_e64 s[6:7], v245, 3
	v_cndmask_b32_e64 v24, v102, v24, s[0:1]
	v_cndmask_b32_e64 v25, v102, v25, s[2:3]
	v_cndmask_b32_e64 v26, v102, v26, s[4:5]
	v_cndmask_b32_e64 v27, v102, v27, s[6:7]
	v_max3_f32 v240, v240, v24, v25
	v_max3_f32 v240, v240, v26, v27
	v_add_u32_e32 v245, 0xffffff9c, v241
	v_cmp_gt_i32_e64 s[0:1], v245, 0
	v_cmp_gt_i32_e64 s[2:3], v245, 1
	v_cmp_gt_i32_e64 s[4:5], v245, 2
	v_cmp_gt_i32_e64 s[6:7], v245, 3
	v_cndmask_b32_e64 v16, v102, v16, s[0:1]
	v_cndmask_b32_e64 v17, v102, v17, s[2:3]
	v_cndmask_b32_e64 v18, v102, v18, s[4:5]
	v_cndmask_b32_e64 v19, v102, v19, s[6:7]
	v_max3_f32 v240, v240, v16, v17
	v_max3_f32 v240, v240, v18, v19
	s_cmp_le_u32 s98, 2
	s_cbranch_scc1 .Lnsa_cs_max_done
	v_add_u32_e32 v245, 0xffffff80, v241
	v_cmp_gt_i32_e64 s[0:1], v245, 0
	v_cmp_gt_i32_e64 s[2:3], v245, 1
	v_cmp_gt_i32_e64 s[4:5], v245, 2
	v_cmp_gt_i32_e64 s[6:7], v245, 3
	v_cndmask_b32_e64 v40, v102, v40, s[0:1]
	v_cndmask_b32_e64 v41, v102, v41, s[2:3]
	v_cndmask_b32_e64 v42, v102, v42, s[4:5]
	v_cndmask_b32_e64 v43, v102, v43, s[6:7]
	v_max3_f32 v240, v240, v40, v41
	v_max3_f32 v240, v240, v42, v43
	v_add_u32_e32 v245, 0xffffff7c, v241
	v_cmp_gt_i32_e64 s[0:1], v245, 0
	v_cmp_gt_i32_e64 s[2:3], v245, 1
	v_cmp_gt_i32_e64 s[4:5], v245, 2
	v_cmp_gt_i32_e64 s[6:7], v245, 3
	v_cndmask_b32_e64 v28, v102, v28, s[0:1]
	v_cndmask_b32_e64 v29, v102, v29, s[2:3]
	v_cndmask_b32_e64 v30, v102, v30, s[4:5]
	v_cndmask_b32_e64 v31, v102, v31, s[6:7]
	v_max3_f32 v240, v240, v28, v29
	v_max3_f32 v240, v240, v30, v31
	v_add_u32_e32 v245, 0xffffff60, v241
	v_cmp_gt_i32_e64 s[0:1], v245, 0
	v_cmp_gt_i32_e64 s[2:3], v245, 1
	v_cmp_gt_i32_e64 s[4:5], v245, 2
	v_cmp_gt_i32_e64 s[6:7], v245, 3
	v_cndmask_b32_e64 v20, v102, v20, s[0:1]
	v_cndmask_b32_e64 v21, v102, v21, s[2:3]
	v_cndmask_b32_e64 v22, v102, v22, s[4:5]
	v_cndmask_b32_e64 v23, v102, v23, s[6:7]
	v_max3_f32 v240, v240, v20, v21
	v_max3_f32 v240, v240, v22, v23
	v_add_u32_e32 v245, 0xffffff5c, v241
	v_cmp_gt_i32_e64 s[0:1], v245, 0
	v_cmp_gt_i32_e64 s[2:3], v245, 1
	v_cmp_gt_i32_e64 s[4:5], v245, 2
	v_cmp_gt_i32_e64 s[6:7], v245, 3
	v_cndmask_b32_e64 v12, v102, v12, s[0:1]
	v_cndmask_b32_e64 v13, v102, v13, s[2:3]
	v_cndmask_b32_e64 v14, v102, v14, s[4:5]
	v_cndmask_b32_e64 v15, v102, v15, s[6:7]
	v_max3_f32 v240, v240, v12, v13
	v_max3_f32 v240, v240, v14, v15
	s_cmp_le_u32 s98, 3
	s_cbranch_scc1 .Lnsa_cs_max_done
	v_add_u32_e32 v245, 0xffffff40, v241
	v_cmp_gt_i32_e64 s[0:1], v245, 0
	v_cmp_gt_i32_e64 s[2:3], v245, 1
	v_cmp_gt_i32_e64 s[4:5], v245, 2
	v_cmp_gt_i32_e64 s[6:7], v245, 3
	v_cndmask_b32_e64 v48, v102, v48, s[0:1]
	v_cndmask_b32_e64 v49, v102, v49, s[2:3]
	v_cndmask_b32_e64 v50, v102, v50, s[4:5]
	v_cndmask_b32_e64 v51, v102, v51, s[6:7]
	v_max3_f32 v240, v240, v48, v49
	v_max3_f32 v240, v240, v50, v51
	v_add_u32_e32 v245, 0xffffff3c, v241
	v_cmp_gt_i32_e64 s[0:1], v245, 0
	v_cmp_gt_i32_e64 s[2:3], v245, 1
	v_cmp_gt_i32_e64 s[4:5], v245, 2
	v_cmp_gt_i32_e64 s[6:7], v245, 3
	v_cndmask_b32_e64 v44, v102, v44, s[0:1]
	v_cndmask_b32_e64 v45, v102, v45, s[2:3]
	v_cndmask_b32_e64 v46, v102, v46, s[4:5]
	v_cndmask_b32_e64 v47, v102, v47, s[6:7]
	v_max3_f32 v240, v240, v44, v45
	v_max3_f32 v240, v240, v46, v47
	v_add_u32_e32 v245, 0xffffff20, v241
	v_cmp_gt_i32_e64 s[0:1], v245, 0
	v_cmp_gt_i32_e64 s[2:3], v245, 1
	v_cmp_gt_i32_e64 s[4:5], v245, 2
	v_cmp_gt_i32_e64 s[6:7], v245, 3
	v_cndmask_b32_e64 v32, v102, v32, s[0:1]
	v_cndmask_b32_e64 v33, v102, v33, s[2:3]
	v_cndmask_b32_e64 v34, v102, v34, s[4:5]
	v_cndmask_b32_e64 v35, v102, v35, s[6:7]
	v_max3_f32 v240, v240, v32, v33
	v_max3_f32 v240, v240, v34, v35
	v_add_u32_e32 v245, 0xffffff1c, v241
	v_cmp_gt_i32_e64 s[0:1], v245, 0
	v_cmp_gt_i32_e64 s[2:3], v245, 1
	v_cmp_gt_i32_e64 s[4:5], v245, 2
	v_cmp_gt_i32_e64 s[6:7], v245, 3
	v_cndmask_b32_e64 v8, v102, v8, s[0:1]
	v_cndmask_b32_e64 v9, v102, v9, s[2:3]
	v_cndmask_b32_e64 v10, v102, v10, s[4:5]
	v_cndmask_b32_e64 v11, v102, v11, s[6:7]
	v_max3_f32 v240, v240, v8, v9
	v_max3_f32 v240, v240, v10, v11
.Lnsa_cs_max_done:
	v_mov_b32_e32 v244, v240
	s_nop 1
	v_permlane16_swap_b32_e32 v244, v240
	v_max_f32_e32 v240, v240, v244
	v_mov_b32_e32 v244, v240
	s_nop 1
	v_permlane32_swap_b32_e32 v244, v240
	v_max_f32_e32 v240, v240, v244
	v_mov_b32_e32 v246, v240
	v_mov_b32_e32 v247, v240
	v_pk_add_f32 v[68:69], v[68:69], v[246:247] neg_lo:[0,1] neg_hi:[0,1]
	v_pk_add_f32 v[70:71], v[70:71], v[246:247] neg_lo:[0,1] neg_hi:[0,1]
	v_exp_f32_e32 v143, v68
	v_exp_f32_e32 v141, v69
	v_exp_f32_e32 v140, v70
	v_exp_f32_e32 v139, v71
	v_pk_add_f32 v[64:65], v[64:65], v[246:247] neg_lo:[0,1] neg_hi:[0,1]
	v_pk_add_f32 v[66:67], v[66:67], v[246:247] neg_lo:[0,1] neg_hi:[0,1]
	v_exp_f32_e32 v138, v64
	v_exp_f32_e32 v137, v65
	v_exp_f32_e32 v136, v66
	v_exp_f32_e32 v135, v67
	v_pk_add_f32 v[60:61], v[60:61], v[246:247] neg_lo:[0,1] neg_hi:[0,1]
	v_pk_add_f32 v[62:63], v[62:63], v[246:247] neg_lo:[0,1] neg_hi:[0,1]
	v_exp_f32_e32 v134, v60
	v_exp_f32_e32 v133, v61
	v_exp_f32_e32 v132, v62
	v_exp_f32_e32 v131, v63
	v_pk_add_f32 v[56:57], v[56:57], v[246:247] neg_lo:[0,1] neg_hi:[0,1]
	v_pk_add_f32 v[58:59], v[58:59], v[246:247] neg_lo:[0,1] neg_hi:[0,1]
	v_exp_f32_e32 v130, v56
	v_exp_f32_e32 v129, v57
	v_exp_f32_e32 v128, v58
	v_exp_f32_e32 v124, v59
	s_cmp_le_u32 s98, 1
	s_cbranch_scc1 .Lnsa_cs_exp_done
	v_pk_add_f32 v[52:53], v[52:53], v[246:247] neg_lo:[0,1] neg_hi:[0,1]
	v_pk_add_f32 v[54:55], v[54:55], v[246:247] neg_lo:[0,1] neg_hi:[0,1]
	v_exp_f32_e32 v65, v52
	v_exp_f32_e32 v62, v53
	v_exp_f32_e32 v126, v54
	v_exp_f32_e32 v71, v55
	v_pk_add_f32 v[36:37], v[36:37], v[246:247] neg_lo:[0,1] neg_hi:[0,1]
	v_pk_add_f32 v[38:39], v[38:39], v[246:247] neg_lo:[0,1] neg_hi:[0,1]
	v_exp_f32_e32 v67, v36
	v_exp_f32_e32 v127, v37
	v_exp_f32_e32 v125, v38
	v_exp_f32_e32 v70, v39
	v_pk_add_f32 v[24:25], v[24:25], v[246:247] neg_lo:[0,1] neg_hi:[0,1]
	v_pk_add_f32 v[26:27], v[26:27], v[246:247] neg_lo:[0,1] neg_hi:[0,1]
	v_exp_f32_e32 v123, v24
	v_exp_f32_e32 v122, v25
	v_exp_f32_e32 v121, v26
	v_exp_f32_e32 v120, v27
	v_pk_add_f32 v[16:17], v[16:17], v[246:247] neg_lo:[0,1] neg_hi:[0,1]
	v_pk_add_f32 v[18:19], v[18:19], v[246:247] neg_lo:[0,1] neg_hi:[0,1]
	v_exp_f32_e32 v119, v16
	v_exp_f32_e32 v69, v17
	v_exp_f32_e32 v68, v18
	v_exp_f32_e32 v66, v19
	s_cmp_le_u32 s98, 2
	s_cbranch_scc1 .Lnsa_cs_exp_done
	v_pk_add_f32 v[40:41], v[40:41], v[246:247] neg_lo:[0,1] neg_hi:[0,1]
	v_pk_add_f32 v[42:43], v[42:43], v[246:247] neg_lo:[0,1] neg_hi:[0,1]
	v_exp_f32_e32 v64, v40
	v_exp_f32_e32 v63, v41
	v_exp_f32_e32 v61, v42
	v_exp_f32_e32 v60, v43
	v_pk_add_f32 v[28:29], v[28:29], v[246:247] neg_lo:[0,1] neg_hi:[0,1]
	v_pk_add_f32 v[30:31], v[30:31], v[246:247] neg_lo:[0,1] neg_hi:[0,1]
	v_exp_f32_e32 v59, v28
	v_exp_f32_e32 v58, v29
	v_exp_f32_e32 v57, v30
	v_exp_f32_e32 v56, v31
	v_pk_add_f32 v[20:21], v[20:21], v[246:247] neg_lo:[0,1] neg_hi:[0,1]
	v_pk_add_f32 v[22:23], v[22:23], v[246:247] neg_lo:[0,1] neg_hi:[0,1]
	v_exp_f32_e32 v55, v20
	v_exp_f32_e32 v54, v21
	v_exp_f32_e32 v53, v22
	v_exp_f32_e32 v52, v23
	v_pk_add_f32 v[12:13], v[12:13], v[246:247] neg_lo:[0,1] neg_hi:[0,1]
	v_pk_add_f32 v[14:15], v[14:15], v[246:247] neg_lo:[0,1] neg_hi:[0,1]
	v_exp_f32_e32 v43, v12
	v_exp_f32_e32 v41, v13
	v_exp_f32_e32 v40, v14
	v_exp_f32_e32 v39, v15
	s_cmp_le_u32 s98, 3
	s_cbranch_scc1 .Lnsa_cs_exp_done
	v_pk_add_f32 v[48:49], v[48:49], v[246:247] neg_lo:[0,1] neg_hi:[0,1]
	v_pk_add_f32 v[50:51], v[50:51], v[246:247] neg_lo:[0,1] neg_hi:[0,1]
	v_exp_f32_e32 v38, v48
	v_exp_f32_e32 v30, v49
	v_exp_f32_e32 v29, v50
	v_exp_f32_e32 v27, v51
	v_pk_add_f32 v[44:45], v[44:45], v[246:247] neg_lo:[0,1] neg_hi:[0,1]
	v_pk_add_f32 v[46:47], v[46:47], v[246:247] neg_lo:[0,1] neg_hi:[0,1]
	v_exp_f32_e32 v26, v44
	v_exp_f32_e32 v24, v45
	v_exp_f32_e32 v22, v46
	v_exp_f32_e32 v21, v47
	v_pk_add_f32 v[32:33], v[32:33], v[246:247] neg_lo:[0,1] neg_hi:[0,1]
	v_pk_add_f32 v[34:35], v[34:35], v[246:247] neg_lo:[0,1] neg_hi:[0,1]
	v_exp_f32_e32 v20, v32
	v_exp_f32_e32 v19, v33
	v_exp_f32_e32 v17, v34
	v_exp_f32_e32 v14, v35
	v_pk_add_f32 v[8:9], v[8:9], v[246:247] neg_lo:[0,1] neg_hi:[0,1]
	v_pk_add_f32 v[10:11], v[10:11], v[246:247] neg_lo:[0,1] neg_hi:[0,1]
	v_exp_f32_e32 v13, v8
	v_exp_f32_e32 v12, v9
	v_exp_f32_e32 v9, v10
	v_exp_f32_e32 v8, v11
.Lnsa_cs_exp_done:
	s_nop 0
	v_add_f32_e32 v10, 0, v143
	v_add_f32_e32 v10, v141, v10
	v_add_f32_e32 v10, v140, v10
	v_add_f32_e32 v10, v139, v10
	v_add_f32_e32 v10, v138, v10
	v_add_f32_e32 v10, v137, v10
	v_add_f32_e32 v10, v136, v10
	v_add_f32_e32 v10, v135, v10
	v_add_f32_e32 v10, v134, v10
	v_add_f32_e32 v10, v133, v10
	v_add_f32_e32 v10, v132, v10
	v_add_f32_e32 v10, v131, v10
	v_add_f32_e32 v10, v130, v10
	v_add_f32_e32 v10, v129, v10
	v_add_f32_e32 v10, v128, v10
	v_add_f32_e32 v10, v124, v10
	s_cmp_le_u32 s98, 1
	s_cbranch_scc1 .Lnsa_cs_sum_done
	v_add_f32_e32 v10, v65, v10
	v_add_f32_e32 v10, v62, v10
	v_add_f32_e32 v10, v126, v10
	v_add_f32_e32 v10, v71, v10
	v_add_f32_e32 v10, v67, v10
	v_add_f32_e32 v10, v127, v10
	v_add_f32_e32 v10, v125, v10
	v_add_f32_e32 v10, v70, v10
	v_add_f32_e32 v10, v123, v10
	v_add_f32_e32 v10, v122, v10
	v_add_f32_e32 v10, v121, v10
	v_add_f32_e32 v10, v120, v10
	v_add_f32_e32 v10, v119, v10
	v_add_f32_e32 v10, v69, v10
	v_add_f32_e32 v10, v68, v10
	v_add_f32_e32 v10, v66, v10
	s_cmp_le_u32 s98, 2
	s_cbranch_scc1 .Lnsa_cs_sum_done
	v_add_f32_e32 v10, v64, v10
	v_add_f32_e32 v10, v63, v10
	v_add_f32_e32 v10, v61, v10
	v_add_f32_e32 v10, v60, v10
	v_add_f32_e32 v10, v59, v10
	v_add_f32_e32 v10, v58, v10
	v_add_f32_e32 v10, v57, v10
	v_add_f32_e32 v10, v56, v10
	v_add_f32_e32 v10, v55, v10
	v_add_f32_e32 v10, v54, v10
	v_add_f32_e32 v10, v53, v10
	v_add_f32_e32 v10, v52, v10
	v_add_f32_e32 v10, v43, v10
	v_add_f32_e32 v10, v41, v10
	v_add_f32_e32 v10, v40, v10
	v_add_f32_e32 v10, v39, v10
	s_cmp_le_u32 s98, 3
	s_cbranch_scc1 .Lnsa_cs_sum_done
	v_add_f32_e32 v10, v38, v10
	v_add_f32_e32 v10, v30, v10
	v_add_f32_e32 v10, v29, v10
	v_add_f32_e32 v10, v27, v10
	v_add_f32_e32 v10, v26, v10
	v_add_f32_e32 v10, v24, v10
	v_add_f32_e32 v10, v22, v10
	v_add_f32_e32 v10, v21, v10
	v_add_f32_e32 v10, v20, v10
	v_add_f32_e32 v10, v19, v10
	v_add_f32_e32 v10, v17, v10
	v_add_f32_e32 v10, v14, v10
	v_add_f32_e32 v10, v13, v10
	v_add_f32_e32 v10, v12, v10
	v_add_f32_e32 v10, v9, v10
	v_add_f32_e32 v10, v8, v10
.Lnsa_cs_sum_done:
	v_mov_b32_e32 v244, v10
	s_nop 1
	v_permlane16_swap_b32_e32 v244, v10
	v_add_f32_e32 v10, v10, v244
	v_mov_b32_e32 v244, v10
	s_nop 1
	v_permlane32_swap_b32_e32 v244, v10
	v_add_f32_e32 v10, v10, v244
	v_div_scale_f32 v11, s[0:1], v10, v10, 1.0
	v_rcp_f32_e32 v15, v11
	s_nop 0
	v_fma_f32 v16, -v11, v15, 1.0
	v_fmac_f32_e32 v15, v16, v15
	v_div_scale_f32 v16, vcc, 1.0, v10, 1.0
	v_mul_f32_e32 v18, v16, v15
	v_fma_f32 v23, -v11, v18, v16
	v_fmac_f32_e32 v18, v23, v15
	v_fma_f32 v11, -v11, v18, v16
	v_div_fmas_f32 v11, v11, v15, v18
	v_div_fixup_f32 v11, v11, v10, 1.0
	v_cmp_lt_f32_e32 vcc, 0, v10
	v_xor_b32_e32 v10, 1, v174
	v_xor_b32_e32 v15, 2, v174
	v_cndmask_b32_e32 v11, 0, v11, vcc
	v_cmp_lt_i32_e32 vcc, v10, v116
	v_lshlrev_b32_e32 v23, 2, v84
	s_nop 0
	v_cndmask_b32_e32 v10, v174, v10, vcc
	v_lshlrev_b32_e32 v36, 2, v10
	v_mul_f32_e32 v10, v143, v11
	s_nop 1
	v_mov_b32_dpp v16, v10 quad_perm:[1,0,3,2] row_mask:0xf bank_mask:0xf
	v_cmp_lt_i32_e32 vcc, v15, v116
	v_fmac_f32_e32 v16, v143, v11
	v_cndmask_b32_e32 v15, v174, v15, vcc
	v_lshlrev_b32_e32 v37, 2, v15
	s_nop 1
	v_mov_b32_dpp v18, v16 quad_perm:[2,3,0,1] row_mask:0xf bank_mask:0xf
	v_or_b32_e32 v15, s15, v88
	v_lshlrev_b32_e32 v15, 10, v15
	v_cmp_eq_u32_e32 vcc, 0, v118
	v_add3_u32 v15, s65, v15, v23
	s_and_saveexec_b64 s[0:1], vcc
	s_cbranch_execz .LBB0_447
	v_add_f32_e32 v16, v16, v18
	ds_write_b32 v15, v16
